# attention softmax: packed f32 subtract and tree row-sum (32 fewer VALU per key tile)
# baseline (speedup 1.0000x reference)
.LBB0_847:
	v_mov_b32_e32 v230, v191
	v_pk_add_f32 v[82:83], v[82:83], v[230:231] op_sel_hi:[1,0] neg_lo:[0,1] neg_hi:[0,1]
	v_pk_add_f32 v[84:85], v[84:85], v[230:231] op_sel_hi:[1,0] neg_lo:[0,1] neg_hi:[0,1]
	v_pk_add_f32 v[86:87], v[86:87], v[230:231] op_sel_hi:[1,0] neg_lo:[0,1] neg_hi:[0,1]
	v_pk_add_f32 v[88:89], v[88:89], v[230:231] op_sel_hi:[1,0] neg_lo:[0,1] neg_hi:[0,1]
	v_exp_f32_e32 v82, v82
	v_exp_f32_e32 v83, v83
	v_exp_f32_e32 v84, v84
	v_exp_f32_e32 v85, v85
	v_exp_f32_e32 v86, v86
	v_exp_f32_e32 v87, v87
	v_exp_f32_e32 v88, v88
	v_exp_f32_e32 v89, v89
	v_cvt_pk_bf16_f32 v222, v82, v83
	v_cvt_pk_bf16_f32 v223, v84, v85
	v_cvt_pk_bf16_f32 v224, v86, v87
	v_cvt_pk_bf16_f32 v225, v88, v89
	v_max_f32_e32 v201, v67, v67
	v_max_f32_e32 v208, v66, v66
	v_mfma_f32_32x32x16_bf16 v[50:65], v[158:161], v[222:225], v[50:65]
	v_max_f32_e32 v201, v208, v201
	v_max3_f32 v201, v201, v68, v69
	v_pk_add_f32 v[90:91], v[90:91], v[230:231] op_sel_hi:[1,0] neg_lo:[0,1] neg_hi:[0,1]
	v_pk_add_f32 v[92:93], v[92:93], v[230:231] op_sel_hi:[1,0] neg_lo:[0,1] neg_hi:[0,1]
	v_pk_add_f32 v[94:95], v[94:95], v[230:231] op_sel_hi:[1,0] neg_lo:[0,1] neg_hi:[0,1]
	v_mfma_f32_32x32x16_bf16 v[34:49], v[138:141], v[222:225], v[34:49]
	v_pk_add_f32 v[96:97], v[96:97], v[230:231] op_sel_hi:[1,0] neg_lo:[0,1] neg_hi:[0,1]
	v_max3_f32 v201, v201, v70, v71
	v_exp_f32_e32 v90, v90
	v_exp_f32_e32 v91, v91
	v_exp_f32_e32 v92, v92
	v_exp_f32_e32 v93, v93
	v_exp_f32_e32 v94, v94
	v_exp_f32_e32 v95, v95
	v_exp_f32_e32 v96, v96
	v_exp_f32_e32 v97, v97
	v_max3_f32 v201, v201, v72, v73
	v_max3_f32 v201, v201, v74, v75
	v_max3_f32 v201, v201, v76, v77
	v_max3_f32 v201, v201, v78, v79
	v_cvt_pk_bf16_f32 v226, v90, v91
	v_cvt_pk_bf16_f32 v227, v92, v93
	v_cvt_pk_bf16_f32 v228, v94, v95
	v_cvt_pk_bf16_f32 v229, v96, v97
	v_max3_f32 v201, v201, v80, v81
	v_mov_b32_e32 v208, v201
	v_mfma_f32_32x32x16_bf16 v[50:65], v[154:157], v[226:229], v[50:65]
	s_nop 0
	v_permlane32_swap_b32_e32 v208, v201
	v_max_f32_e32 v201, v201, v208
	v_add_f32_e32 v208, 0x41000000, v221
	v_cmp_gt_f32_e32 vcc, v201, v208
	v_mfma_f32_32x32x16_bf16 v[34:49], v[130:133], v[226:229], v[34:49]
	s_cbranch_vccz .LBB0_849
	v_max_f32_e32 v201, v201, v201
	v_max_f32_e32 v208, v221, v221
	v_max_f32_e32 v201, v208, v201
	v_sub_f32_e32 v208, v221, v201
	v_exp_f32_e32 v222, v208
	v_mov_b32_e32 v221, v201
	v_mul_f32_e32 v193, v193, v222
	v_pk_mul_f32 v[32:33], v[32:33], v[222:223] op_sel_hi:[1,0]
	v_pk_mul_f32 v[30:31], v[30:31], v[222:223] op_sel_hi:[1,0]
	v_pk_mul_f32 v[28:29], v[28:29], v[222:223] op_sel_hi:[1,0]
	v_pk_mul_f32 v[26:27], v[26:27], v[222:223] op_sel_hi:[1,0]
	v_pk_mul_f32 v[24:25], v[24:25], v[222:223] op_sel_hi:[1,0]
	v_pk_mul_f32 v[22:23], v[22:23], v[222:223] op_sel_hi:[1,0]
	v_pk_mul_f32 v[20:21], v[20:21], v[222:223] op_sel_hi:[1,0]
	v_pk_mul_f32 v[18:19], v[18:19], v[222:223] op_sel_hi:[1,0]
	v_pk_mul_f32 v[16:17], v[16:17], v[222:223] op_sel_hi:[1,0]
	v_pk_mul_f32 v[14:15], v[14:15], v[222:223] op_sel_hi:[1,0]
	v_pk_mul_f32 v[12:13], v[12:13], v[222:223] op_sel_hi:[1,0]
	v_pk_mul_f32 v[10:11], v[10:11], v[222:223] op_sel_hi:[1,0]
	v_pk_mul_f32 v[8:9], v[8:9], v[222:223] op_sel_hi:[1,0]
	v_pk_mul_f32 v[6:7], v[6:7], v[222:223] op_sel_hi:[1,0]
	v_pk_mul_f32 v[4:5], v[4:5], v[222:223] op_sel_hi:[1,0]
	v_pk_mul_f32 v[2:3], v[2:3], v[222:223] op_sel_hi:[1,0]
.LBB0_849:
	v_mov_b32_e32 v234, v221
	v_pk_add_f32 v[66:67], v[66:67], v[234:235] op_sel_hi:[1,0] neg_lo:[0,1] neg_hi:[0,1]
	v_exp_f32_e32 v66, v66
	v_exp_f32_e32 v67, v67
	v_pk_add_f32 v[68:69], v[68:69], v[234:235] op_sel_hi:[1,0] neg_lo:[0,1] neg_hi:[0,1]
	v_exp_f32_e32 v68, v68
	v_pk_add_f32 v[70:71], v[70:71], v[234:235] op_sel_hi:[1,0] neg_lo:[0,1] neg_hi:[0,1]
	v_pk_add_f32 v[72:73], v[72:73], v[234:235] op_sel_hi:[1,0] neg_lo:[0,1] neg_hi:[0,1]
	v_exp_f32_e32 v69, v69
	v_exp_f32_e32 v70, v70
	v_exp_f32_e32 v71, v71
	v_exp_f32_e32 v72, v72
	v_exp_f32_e32 v73, v73
	v_pk_add_f32 v[82:83], v[82:83], v[84:85]
	v_pk_add_f32 v[86:87], v[86:87], v[88:89]
	v_pk_add_f32 v[90:91], v[90:91], v[92:93]
	v_pk_add_f32 v[94:95], v[94:95], v[96:97]
	v_pk_add_f32 v[82:83], v[82:83], v[86:87]
	v_pk_add_f32 v[90:91], v[90:91], v[94:95]
	v_pk_add_f32 v[82:83], v[82:83], v[90:91]
	v_add_f32_e32 v82, v82, v83
	v_add_f32_e32 v220, v220, v82
	v_pk_add_f32 v[82:83], v[66:67], v[68:69]
	v_cvt_pk_bf16_f32 v66, v66, v67
	v_cvt_pk_bf16_f32 v67, v68, v69
	v_cvt_pk_bf16_f32 v68, v70, v71
	v_cvt_pk_bf16_f32 v69, v72, v73
	v_pk_add_f32 v[74:75], v[74:75], v[234:235] op_sel_hi:[1,0] neg_lo:[0,1] neg_hi:[0,1]
	v_pk_add_f32 v[76:77], v[76:77], v[234:235] op_sel_hi:[1,0] neg_lo:[0,1] neg_hi:[0,1]
	v_mfma_f32_32x32x16_bf16 v[18:33], v[158:161], v[66:69], v[18:33]
	v_pk_add_f32 v[78:79], v[78:79], v[234:235] op_sel_hi:[1,0] neg_lo:[0,1] neg_hi:[0,1]
	v_pk_add_f32 v[80:81], v[80:81], v[234:235] op_sel_hi:[1,0] neg_lo:[0,1] neg_hi:[0,1]
	v_mfma_f32_32x32x16_bf16 v[2:17], v[138:141], v[66:69], v[2:17]
	v_exp_f32_e32 v74, v74
	v_exp_f32_e32 v75, v75
	v_exp_f32_e32 v76, v76
	v_exp_f32_e32 v77, v77
	v_exp_f32_e32 v78, v78
	v_exp_f32_e32 v79, v79
	v_exp_f32_e32 v80, v80
	v_exp_f32_e32 v81, v81
	v_pk_add_f32 v[84:85], v[70:71], v[72:73]
	v_cvt_pk_bf16_f32 v70, v74, v75
	v_cvt_pk_bf16_f32 v71, v76, v77
	v_cvt_pk_bf16_f32 v72, v78, v79
	v_cvt_pk_bf16_f32 v73, v80, v81
	v_pk_add_f32 v[86:87], v[74:75], v[76:77]
	v_pk_add_f32 v[88:89], v[78:79], v[80:81]
	v_mfma_f32_32x32x16_bf16 v[18:33], v[154:157], v[70:73], v[18:33]
	v_pk_add_f32 v[82:83], v[82:83], v[84:85]
	v_pk_add_f32 v[86:87], v[86:87], v[88:89]
	v_pk_add_f32 v[82:83], v[82:83], v[86:87]
	v_add_f32_e32 v82, v82, v83
	v_add_f32_e32 v193, v193, v82
	v_subrev_u32_e32 v195, 32, v195
	v_mfma_f32_32x32x16_bf16 v[2:17], v[130:133], v[70:73], v[2:17]
	s_and_b64 vcc, exec, s[46:47]
	s_cbranch_vccnz .LBB0_836
	s_waitcnt vmcnt(4)
	v_mov_b64_e32 v[130:131], v[174:175]
	v_mov_b64_e32 v[138:139], v[170:171]
	v_mov_b64_e32 v[154:155], v[166:167]
	v_mov_b64_e32 v[158:159], v[162:163]
	v_mov_b64_e32 v[132:133], v[176:177]
	v_mov_b64_e32 v[140:141], v[172:173]
	v_mov_b64_e32 v[156:157], v[168:169]
	v_mov_b64_e32 v[160:161], v[164:165]
	s_branch .LBB0_843
